# hoist far-tile QK2 MFMAs above max1 in MODE0 prompt attention; in-proj fused-norm epilogue loads rs/shw once per unit
# baseline (speedup 1.0000x reference)
;     __device__ __forceinline__ void operator()(const f32x4 (&acc)[2][2][4][2], const Unit& u, int wr, int wc, int fr, int fq) const {
;     ...
;             const int c0 = u.pn * 256 + bj * 128 + wc * 32 + 8 * fq;
;             if (c0 >= INC) continue;
; #pragma unroll
;             for (int ai = 0; ai < 2; ++ai)
; #pragma unroll
;                 for (int m = 0; m < 4; ++m) {
;                     const int r = EPI_ROW(u, ai, wr, m, fr);
;                     f32x4 v0 = acc[ai][bj][m][0], v1 = acc[ai][bj][m][1];
;                     if (rs) {
;                         const float rstd = rsqrtf(rs[r] * (1.f / 1024.f) + EPS);
;                         const float* sp = shw + (size_t)batch_of(r) * INPAD + c0;
;                         v0 = v0 * rstd + *(const f32x4*)sp; v1 = v1 * rstd + *(const f32x4*)(sp + 4);
.LBB0_238:
	s_lshl_b32 s24, s10, 8
	v_or_b32_e32 v4, s24, v153
	s_movk_i32 s2, 0x720
	v_cmp_gt_i32_e32 vcc, s2, v4
	v_ashrrev_i32_e32 v7, 31, v4
	s_and_saveexec_b64 s[54:55], vcc
	s_cbranch_execz .LBB0_342
	s_lshl_b32 s25, s69, 8
	s_add_i32 s70, s25, s4
	v_or_b32_e32 v146, s70, v141
	v_cndmask_b32_e64 v148, 0, 1, s[72:73]
	v_mov_b32_e32 v6, v4
	v_ashrrev_i32_e32 v147, 31, v146
	v_cmp_ne_u32_e64 s[40:41], 1, v148
	s_andn2_b64 vcc, exec, s[72:73]
	v_cmp_gt_i32_e64 s[42:43], s89, v146
	s_cbranch_vccnz .LBB0_241
	v_readlane_b32 s2, v251, 45
	v_readlane_b32 s3, v251, 46
	s_nop 1
	v_lshl_add_u64 v[148:149], v[146:147], 2, s[2:3]
	global_load_dword v162, v[148:149], off
	global_load_dword v232, v[148:149], off
	global_load_dword v233, v[148:149], off offset:64
	global_load_dword v234, v[148:149], off offset:128
	global_load_dword v235, v[148:149], off offset:192
	global_load_dword v236, v[148:149], off offset:512
	global_load_dword v237, v[148:149], off offset:576
	global_load_dword v238, v[148:149], off offset:640
	global_load_dword v239, v[148:149], off offset:704
	s_add_i32 s3, s70, 0xffff0000
	s_lshr_b32 s3, s3, 6
	s_ashr_i32 s2, s70, 12
	s_add_i32 s3, s3, 16
	v_mov_b32_e32 v148, s3
	v_mov_b32_e32 v149, s2
	v_cndmask_b32_e64 v148, v148, v149, s[42:43]
	v_ashrrev_i32_e32 v149, 31, v148
	v_lshlrev_b64 v[148:149], 13, v[148:149]
	v_lshl_add_u64 v[148:149], s[56:57], 0, v[148:149]
	v_lshl_add_u64 v[158:159], v[6:7], 2, v[148:149]
	global_load_dwordx4 v[148:151], v[158:159], off
	s_nop 0
	global_load_dwordx4 v[158:161], v[158:159], off offset:16
	s_waitcnt vmcnt(0)
	v_mov_b32_e32 v240, v148
	v_mov_b32_e32 v241, v149
	v_mov_b32_e32 v242, v150
	v_mov_b32_e32 v243, v151
	v_mov_b32_e32 v244, v158
	v_mov_b32_e32 v245, v159
	v_mov_b32_e32 v246, v160
	v_mov_b32_e32 v247, v161
	v_fmamk_f32 v162, v162, 0x3a800000, v214
	v_mul_f32_e32 v163, 0x4b800000, v162
	v_cmp_gt_f32_e32 vcc, s9, v162
	s_nop 1
	v_cndmask_b32_e32 v162, v162, v163, vcc
	v_rsq_f32_e32 v162, v162
	s_nop 0
	v_mul_f32_e32 v163, 0x45800000, v162
	v_cndmask_b32_e32 v162, v162, v163, vcc
	v_pk_fma_f32 v[130:131], v[130:131], v[162:163], v[150:151] op_sel_hi:[1,0,1]
	v_pk_fma_f32 v[128:129], v[128:129], v[162:163], v[148:149] op_sel_hi:[1,0,1]
	v_pk_fma_f32 v[126:127], v[126:127], v[162:163], v[160:161] op_sel_hi:[1,0,1]
	v_pk_fma_f32 v[124:125], v[124:125], v[162:163], v[158:159] op_sel_hi:[1,0,1]

;     __device__ __forceinline__ void operator()(const f32x4 (&acc)[2][2][4][2], const Unit& u, int wr, int wc, int fr, int fq) const {
;     ...
;                     const int r = EPI_ROW(u, ai, wr, m, fr);
;                     f32x4 v0 = acc[ai][bj][m][0], v1 = acc[ai][bj][m][1];
;                     if (rs) {
;                         const float rstd = rsqrtf(rs[r] * (1.f / 1024.f) + EPS);
;                         const float* sp = shw + (size_t)batch_of(r) * INPAD + c0;
;                         v0 = v0 * rstd + *(const f32x4*)sp; v1 = v1 * rstd + *(const f32x4*)(sp + 4);
.LBB0_252:
	s_nop 1
	v_or_b32_e32 v124, s70, v154
	v_ashrrev_i32_e32 v125, 31, v124
	s_and_b64 vcc, exec, s[40:41]
	v_cmp_gt_i32_e64 s[42:43], s89, v124
	s_cbranch_vccnz .LBB0_254
	v_readlane_b32 s18, v251, 45
	v_readlane_b32 s19, v251, 46
	s_nop 1
	v_lshl_add_u64 v[126:127], v[124:125], 2, s[18:19]
	s_nop 0
	s_add_i32 s19, s70, 0xffff0000
	s_lshr_b32 s19, s19, 6
	s_ashr_i32 s18, s70, 12
	s_add_i32 s19, s19, 16
	v_mov_b32_e32 v126, s19
	v_mov_b32_e32 v127, s18
	v_cndmask_b32_e64 v126, v126, v127, s[42:43]
	v_ashrrev_i32_e32 v127, 31, v126
	v_lshlrev_b64 v[126:127], 13, v[126:127]
	v_lshl_add_u64 v[126:127], s[56:57], 0, v[126:127]
	v_lshl_add_u64 v[130:131], v[6:7], 2, v[126:127]
	s_nop 0
	s_nop 0
	v_mov_b32_e32 v150, v233
	v_mov_b32_e32 v126, v240
	v_mov_b32_e32 v127, v241
	v_mov_b32_e32 v128, v242
	v_mov_b32_e32 v129, v243
	v_mov_b32_e32 v146, v244
	v_mov_b32_e32 v147, v245
	v_mov_b32_e32 v148, v246
	v_mov_b32_e32 v149, v247
	v_fmamk_f32 v130, v150, 0x3a800000, v214
	v_mul_f32_e32 v131, 0x4b800000, v130
	v_cmp_gt_f32_e32 vcc, s9, v130
	s_nop 1
	v_cndmask_b32_e32 v130, v130, v131, vcc
	v_rsq_f32_e32 v130, v130
	s_nop 0
	v_mul_f32_e32 v131, 0x45800000, v130
	v_cndmask_b32_e32 v130, v130, v131, vcc
	v_pk_fma_f32 v[122:123], v[122:123], v[130:131], v[128:129] op_sel_hi:[1,0,1]
	v_pk_fma_f32 v[120:121], v[120:121], v[130:131], v[126:127] op_sel_hi:[1,0,1]
	v_pk_fma_f32 v[118:119], v[118:119], v[130:131], v[148:149] op_sel_hi:[1,0,1]
	v_pk_fma_f32 v[116:117], v[116:117], v[130:131], v[146:147] op_sel_hi:[1,0,1]

;     __device__ __forceinline__ void operator()(const f32x4 (&acc)[2][2][4][2], const Unit& u, int wr, int wc, int fr, int fq) const {
;     ...
;                     const int r = EPI_ROW(u, ai, wr, m, fr);
;                     f32x4 v0 = acc[ai][bj][m][0], v1 = acc[ai][bj][m][1];
;                     if (rs) {
;                         const float rstd = rsqrtf(rs[r] * (1.f / 1024.f) + EPS);
;                         const float* sp = shw + (size_t)batch_of(r) * INPAD + c0;
;                         v0 = v0 * rstd + *(const f32x4*)sp; v1 = v1 * rstd + *(const f32x4*)(sp + 4);
.LBB0_262:
	s_nop 1
	v_or_b32_e32 v116, s70, v155
	v_ashrrev_i32_e32 v117, 31, v116
	s_and_b64 vcc, exec, s[40:41]
	v_cmp_gt_i32_e64 s[44:45], s89, v116
	s_cbranch_vccnz .LBB0_264
	v_readlane_b32 s2, v251, 45
	v_readlane_b32 s3, v251, 46
	s_nop 1
	v_lshl_add_u64 v[118:119], v[116:117], 2, s[2:3]
	s_nop 0
	s_add_i32 s3, s70, 0xffff0000
	s_lshr_b32 s3, s3, 6
	s_ashr_i32 s2, s70, 12
	s_add_i32 s3, s3, 16
	v_mov_b32_e32 v118, s3
	v_mov_b32_e32 v119, s2
	v_cndmask_b32_e64 v118, v118, v119, s[44:45]
	v_ashrrev_i32_e32 v119, 31, v118
	v_lshlrev_b64 v[118:119], 13, v[118:119]
	v_lshl_add_u64 v[118:119], s[56:57], 0, v[118:119]
	v_lshl_add_u64 v[122:123], v[6:7], 2, v[118:119]
	s_nop 0
	s_nop 0
	s_nop 0
	v_mov_b32_e32 v126, v234
	v_mov_b32_e32 v118, v240
	v_mov_b32_e32 v119, v241
	v_mov_b32_e32 v120, v242
	v_mov_b32_e32 v121, v243
	v_mov_b32_e32 v122, v244
	v_mov_b32_e32 v123, v245
	v_mov_b32_e32 v124, v246
	v_mov_b32_e32 v125, v247
	v_fmamk_f32 v126, v126, 0x3a800000, v214
	v_mul_f32_e32 v127, 0x4b800000, v126
	v_cmp_gt_f32_e32 vcc, s9, v126
	s_nop 1
	v_cndmask_b32_e32 v126, v126, v127, vcc
	v_rsq_f32_e32 v126, v126
	s_nop 0
	v_mul_f32_e32 v127, 0x45800000, v126
	v_cndmask_b32_e32 v126, v126, v127, vcc
	v_pk_fma_f32 v[114:115], v[114:115], v[126:127], v[120:121] op_sel_hi:[1,0,1]
	v_pk_fma_f32 v[112:113], v[112:113], v[126:127], v[118:119] op_sel_hi:[1,0,1]
	v_pk_fma_f32 v[110:111], v[110:111], v[126:127], v[124:125] op_sel_hi:[1,0,1]
	v_pk_fma_f32 v[108:109], v[108:109], v[126:127], v[122:123] op_sel_hi:[1,0,1]

;     __device__ __forceinline__ void operator()(const f32x4 (&acc)[2][2][4][2], const Unit& u, int wr, int wc, int fr, int fq) const {
;     ...
;                     const int r = EPI_ROW(u, ai, wr, m, fr);
;                     f32x4 v0 = acc[ai][bj][m][0], v1 = acc[ai][bj][m][1];
;                     if (rs) {
;                         const float rstd = rsqrtf(rs[r] * (1.f / 1024.f) + EPS);
;                         const float* sp = shw + (size_t)batch_of(r) * INPAD + c0;
;                         v0 = v0 * rstd + *(const f32x4*)sp; v1 = v1 * rstd + *(const f32x4*)(sp + 4);
.LBB0_272:
	s_nop 1
	v_or_b32_e32 v108, s70, v156
	v_ashrrev_i32_e32 v109, 31, v108
	s_and_b64 vcc, exec, s[40:41]
	v_cmp_gt_i32_e64 s[44:45], s89, v108
	s_cbranch_vccnz .LBB0_274
	v_readlane_b32 s2, v251, 45
	v_readlane_b32 s3, v251, 46
	s_nop 1
	v_lshl_add_u64 v[110:111], v[108:109], 2, s[2:3]
	s_nop 0
	s_add_i32 s3, s70, 0xffff0000
	s_lshr_b32 s3, s3, 6
	s_ashr_i32 s2, s70, 12
	s_add_i32 s3, s3, 16
	v_mov_b32_e32 v110, s3
	v_mov_b32_e32 v111, s2
	v_cndmask_b32_e64 v110, v110, v111, s[44:45]
	v_ashrrev_i32_e32 v111, 31, v110
	v_lshlrev_b64 v[110:111], 13, v[110:111]
	v_lshl_add_u64 v[110:111], s[56:57], 0, v[110:111]
	v_lshl_add_u64 v[114:115], v[6:7], 2, v[110:111]
	s_nop 0
	s_nop 0
	s_nop 0
	v_mov_b32_e32 v118, v235
	v_mov_b32_e32 v110, v240
	v_mov_b32_e32 v111, v241
	v_mov_b32_e32 v112, v242
	v_mov_b32_e32 v113, v243
	v_mov_b32_e32 v114, v244
	v_mov_b32_e32 v115, v245
	v_mov_b32_e32 v116, v246
	v_mov_b32_e32 v117, v247
	v_fmamk_f32 v118, v118, 0x3a800000, v214
	v_mul_f32_e32 v119, 0x4b800000, v118
	v_cmp_gt_f32_e32 vcc, s9, v118
	s_nop 1
	v_cndmask_b32_e32 v118, v118, v119, vcc
	v_rsq_f32_e32 v118, v118
	s_nop 0
	v_mul_f32_e32 v119, 0x45800000, v118
	v_cndmask_b32_e32 v118, v118, v119, vcc
	v_pk_fma_f32 v[106:107], v[106:107], v[118:119], v[112:113] op_sel_hi:[1,0,1]
	v_pk_fma_f32 v[104:105], v[104:105], v[118:119], v[110:111] op_sel_hi:[1,0,1]
	v_pk_fma_f32 v[102:103], v[102:103], v[118:119], v[116:117] op_sel_hi:[1,0,1]
	v_pk_fma_f32 v[100:101], v[100:101], v[118:119], v[114:115] op_sel_hi:[1,0,1]

;     __device__ __forceinline__ void operator()(const f32x4 (&acc)[2][2][4][2], const Unit& u, int wr, int wc, int fr, int fq) const {
;     ...
;                     const int r = EPI_ROW(u, ai, wr, m, fr);
;                     f32x4 v0 = acc[ai][bj][m][0], v1 = acc[ai][bj][m][1];
;                     if (rs) {
;                         const float rstd = rsqrtf(rs[r] * (1.f / 1024.f) + EPS);
;                         const float* sp = shw + (size_t)batch_of(r) * INPAD + c0;
;                         v0 = v0 * rstd + *(const f32x4*)sp; v1 = v1 * rstd + *(const f32x4*)(sp + 4);
.LBB0_292:
	s_or_b64 exec, exec, s[44:45]
	s_add_i32 s25, s25, s77
	v_or_b32_e32 v100, s25, v141
	v_ashrrev_i32_e32 v101, 31, v100
	s_and_b64 vcc, exec, s[40:41]
	v_cmp_gt_i32_e64 s[44:45], s89, v100
	s_cbranch_vccnz .LBB0_294
	v_readlane_b32 s18, v251, 45
	v_readlane_b32 s19, v251, 46
	s_nop 1
	v_lshl_add_u64 v[102:103], v[100:101], 2, s[18:19]
	s_nop 0
	s_add_i32 s19, s25, 0xffff0000
	s_lshr_b32 s19, s19, 6
	s_ashr_i32 s18, s25, 12
	s_add_i32 s19, s19, 16
	v_mov_b32_e32 v102, s19
	v_mov_b32_e32 v103, s18
	v_cndmask_b32_e64 v102, v102, v103, s[44:45]
	v_ashrrev_i32_e32 v103, 31, v102
	v_lshlrev_b64 v[102:103], 13, v[102:103]
	v_lshl_add_u64 v[102:103], s[56:57], 0, v[102:103]
	v_lshl_add_u64 v[106:107], v[6:7], 2, v[102:103]
	s_nop 0
	s_nop 0
	s_nop 0
	v_mov_b32_e32 v110, v236
	v_mov_b32_e32 v102, v240
	v_mov_b32_e32 v103, v241
	v_mov_b32_e32 v104, v242
	v_mov_b32_e32 v105, v243
	v_mov_b32_e32 v106, v244
	v_mov_b32_e32 v107, v245
	v_mov_b32_e32 v108, v246
	v_mov_b32_e32 v109, v247
	v_fmamk_f32 v110, v110, 0x3a800000, v214
	v_mul_f32_e32 v111, 0x4b800000, v110
	v_cmp_gt_f32_e32 vcc, s9, v110
	s_nop 1
	v_cndmask_b32_e32 v110, v110, v111, vcc
	v_rsq_f32_e32 v110, v110
	s_nop 0
	v_mul_f32_e32 v111, 0x45800000, v110
	v_cndmask_b32_e32 v110, v110, v111, vcc
	v_pk_fma_f32 v[98:99], v[98:99], v[110:111], v[104:105] op_sel_hi:[1,0,1]
	v_pk_fma_f32 v[96:97], v[96:97], v[110:111], v[102:103] op_sel_hi:[1,0,1]
	v_pk_fma_f32 v[94:95], v[94:95], v[110:111], v[108:109] op_sel_hi:[1,0,1]
	v_pk_fma_f32 v[92:93], v[92:93], v[110:111], v[106:107] op_sel_hi:[1,0,1]

;     __device__ __forceinline__ void operator()(const f32x4 (&acc)[2][2][4][2], const Unit& u, int wr, int wc, int fr, int fq) const {
;     ...
;                     const int r = EPI_ROW(u, ai, wr, m, fr);
;                     f32x4 v0 = acc[ai][bj][m][0], v1 = acc[ai][bj][m][1];
;                     if (rs) {
;                         const float rstd = rsqrtf(rs[r] * (1.f / 1024.f) + EPS);
;                         const float* sp = shw + (size_t)batch_of(r) * INPAD + c0;
;                         v0 = v0 * rstd + *(const f32x4*)sp; v1 = v1 * rstd + *(const f32x4*)(sp + 4);
.LBB0_302:
	s_nop 1
	v_or_b32_e32 v92, s25, v154
	v_ashrrev_i32_e32 v93, 31, v92
	s_and_b64 vcc, exec, s[40:41]
	v_cmp_gt_i32_e64 s[44:45], s89, v92
	s_cbranch_vccnz .LBB0_304
	v_readlane_b32 s18, v251, 45
	v_readlane_b32 s19, v251, 46
	s_nop 1
	v_lshl_add_u64 v[94:95], v[92:93], 2, s[18:19]
	s_nop 0
	s_add_i32 s19, s25, 0xffff0000
	s_lshr_b32 s19, s19, 6
	s_ashr_i32 s18, s25, 12
	s_add_i32 s19, s19, 16
	v_mov_b32_e32 v94, s19
	v_mov_b32_e32 v95, s18
	v_cndmask_b32_e64 v94, v94, v95, s[44:45]
	v_ashrrev_i32_e32 v95, 31, v94
	v_lshlrev_b64 v[94:95], 13, v[94:95]
	v_lshl_add_u64 v[94:95], s[56:57], 0, v[94:95]
	v_lshl_add_u64 v[98:99], v[6:7], 2, v[94:95]
	s_nop 0
	s_nop 0
	s_nop 0
	v_mov_b32_e32 v102, v237
	v_mov_b32_e32 v94, v240
	v_mov_b32_e32 v95, v241
	v_mov_b32_e32 v96, v242
	v_mov_b32_e32 v97, v243
	v_mov_b32_e32 v98, v244
	v_mov_b32_e32 v99, v245
	v_mov_b32_e32 v100, v246
	v_mov_b32_e32 v101, v247
	v_fmamk_f32 v102, v102, 0x3a800000, v214
	v_mul_f32_e32 v103, 0x4b800000, v102
	v_cmp_gt_f32_e32 vcc, s9, v102
	s_nop 1
	v_cndmask_b32_e32 v102, v102, v103, vcc
	v_rsq_f32_e32 v102, v102
	s_nop 0
	v_mul_f32_e32 v103, 0x45800000, v102
	v_cndmask_b32_e32 v102, v102, v103, vcc
	v_pk_fma_f32 v[90:91], v[90:91], v[102:103], v[96:97] op_sel_hi:[1,0,1]
	v_pk_fma_f32 v[88:89], v[88:89], v[102:103], v[94:95] op_sel_hi:[1,0,1]
	v_pk_fma_f32 v[86:87], v[86:87], v[102:103], v[100:101] op_sel_hi:[1,0,1]
	v_pk_fma_f32 v[84:85], v[84:85], v[102:103], v[98:99] op_sel_hi:[1,0,1]

;     __device__ __forceinline__ void operator()(const f32x4 (&acc)[2][2][4][2], const Unit& u, int wr, int wc, int fr, int fq) const {
;     ...
;                     const int r = EPI_ROW(u, ai, wr, m, fr);
;                     f32x4 v0 = acc[ai][bj][m][0], v1 = acc[ai][bj][m][1];
;                     if (rs) {
;                         const float rstd = rsqrtf(rs[r] * (1.f / 1024.f) + EPS);
;                         const float* sp = shw + (size_t)batch_of(r) * INPAD + c0;
;                         v0 = v0 * rstd + *(const f32x4*)sp; v1 = v1 * rstd + *(const f32x4*)(sp + 4);
.LBB0_312:
	s_nop 1
	v_or_b32_e32 v84, s25, v155
	v_ashrrev_i32_e32 v85, 31, v84
	s_and_b64 vcc, exec, s[40:41]
	v_cmp_gt_i32_e64 s[44:45], s89, v84
	s_cbranch_vccnz .LBB0_314
	v_readlane_b32 s18, v251, 45
	v_readlane_b32 s19, v251, 46
	s_nop 1
	v_lshl_add_u64 v[86:87], v[84:85], 2, s[18:19]
	s_nop 0
	s_add_i32 s19, s25, 0xffff0000
	s_lshr_b32 s19, s19, 6
	s_ashr_i32 s18, s25, 12
	s_add_i32 s19, s19, 16
	v_mov_b32_e32 v86, s19
	v_mov_b32_e32 v87, s18
	v_cndmask_b32_e64 v86, v86, v87, s[44:45]
	v_ashrrev_i32_e32 v87, 31, v86
	v_lshlrev_b64 v[86:87], 13, v[86:87]
	v_lshl_add_u64 v[86:87], s[56:57], 0, v[86:87]
	v_lshl_add_u64 v[90:91], v[6:7], 2, v[86:87]
	s_nop 0
	s_nop 0
	s_nop 0
	v_mov_b32_e32 v94, v238
	v_mov_b32_e32 v86, v240
	v_mov_b32_e32 v87, v241
	v_mov_b32_e32 v88, v242
	v_mov_b32_e32 v89, v243
	v_mov_b32_e32 v90, v244
	v_mov_b32_e32 v91, v245
	v_mov_b32_e32 v92, v246
	v_mov_b32_e32 v93, v247
	v_fmamk_f32 v94, v94, 0x3a800000, v214
	v_mul_f32_e32 v95, 0x4b800000, v94
	v_cmp_gt_f32_e32 vcc, s9, v94
	s_nop 1
	v_cndmask_b32_e32 v94, v94, v95, vcc
	v_rsq_f32_e32 v94, v94
	s_nop 0
	v_mul_f32_e32 v95, 0x45800000, v94
	v_cndmask_b32_e32 v94, v94, v95, vcc
	v_pk_fma_f32 v[82:83], v[82:83], v[94:95], v[88:89] op_sel_hi:[1,0,1]
	v_pk_fma_f32 v[80:81], v[80:81], v[94:95], v[86:87] op_sel_hi:[1,0,1]
	v_pk_fma_f32 v[78:79], v[78:79], v[94:95], v[92:93] op_sel_hi:[1,0,1]
	v_pk_fma_f32 v[76:77], v[76:77], v[94:95], v[90:91] op_sel_hi:[1,0,1]

;     __device__ __forceinline__ void operator()(const f32x4 (&acc)[2][2][4][2], const Unit& u, int wr, int wc, int fr, int fq) const {
;     ...
;                     const int r = EPI_ROW(u, ai, wr, m, fr);
;                     f32x4 v0 = acc[ai][bj][m][0], v1 = acc[ai][bj][m][1];
;                     if (rs) {
;                         const float rstd = rsqrtf(rs[r] * (1.f / 1024.f) + EPS);
;                         const float* sp = shw + (size_t)batch_of(r) * INPAD + c0;
;                         v0 = v0 * rstd + *(const f32x4*)sp; v1 = v1 * rstd + *(const f32x4*)(sp + 4);
.LBB0_322:
	s_nop 1
	v_or_b32_e32 v76, s25, v156
	v_ashrrev_i32_e32 v77, 31, v76
	s_and_b64 vcc, exec, s[40:41]
	v_cmp_gt_i32_e64 s[40:41], s89, v76
	s_cbranch_vccnz .LBB0_324
	v_readlane_b32 s6, v251, 45
	v_readlane_b32 s7, v251, 46
	s_nop 1
	v_lshl_add_u64 v[78:79], v[76:77], 2, s[6:7]
	s_nop 0
	s_add_i32 s7, s25, 0xffff0000
	s_lshr_b32 s7, s7, 6
	s_ashr_i32 s6, s25, 12
	s_add_i32 s7, s7, 16
	v_mov_b32_e32 v78, s7
	v_mov_b32_e32 v79, s6
	v_cndmask_b32_e64 v78, v78, v79, s[40:41]
	v_ashrrev_i32_e32 v79, 31, v78
	v_lshlrev_b64 v[78:79], 13, v[78:79]
	v_lshl_add_u64 v[78:79], s[56:57], 0, v[78:79]
	v_lshl_add_u64 v[82:83], v[6:7], 2, v[78:79]
	s_nop 0
	s_nop 0
	s_nop 0
	v_mov_b32_e32 v86, v239
	v_mov_b32_e32 v78, v240
	v_mov_b32_e32 v79, v241
	v_mov_b32_e32 v80, v242
	v_mov_b32_e32 v81, v243
	v_mov_b32_e32 v82, v244
	v_mov_b32_e32 v83, v245
	v_mov_b32_e32 v84, v246
	v_mov_b32_e32 v85, v247
	v_fmamk_f32 v86, v86, 0x3a800000, v214
	v_mul_f32_e32 v87, 0x4b800000, v86
	v_cmp_gt_f32_e32 vcc, s9, v86
	s_nop 1
	v_cndmask_b32_e32 v86, v86, v87, vcc
	v_rsq_f32_e32 v86, v86
	s_nop 0
	v_mul_f32_e32 v87, 0x45800000, v86
	v_cndmask_b32_e32 v86, v86, v87, vcc
	v_pk_fma_f32 v[74:75], v[74:75], v[86:87], v[80:81] op_sel_hi:[1,0,1]
	v_pk_fma_f32 v[72:73], v[72:73], v[86:87], v[78:79] op_sel_hi:[1,0,1]
	v_pk_fma_f32 v[70:71], v[70:71], v[86:87], v[84:85] op_sel_hi:[1,0,1]
	v_pk_fma_f32 v[68:69], v[68:69], v[86:87], v[82:83] op_sel_hi:[1,0,1]

;     __device__ __forceinline__ void operator()(const f32x4 (&acc)[2][2][4][2], const Unit& u, int wr, int wc, int fr, int fq) const {
;     ...
;         for (int bj = 0; bj < 2; ++bj) {
;             const int c0 = u.pn * 256 + bj * 128 + wc * 32 + 8 * fq;
;             if (c0 >= INC) continue;
; #pragma unroll
;             for (int ai = 0; ai < 2; ++ai)
; #pragma unroll
;                 for (int m = 0; m < 4; ++m) {
;                     const int r = EPI_ROW(u, ai, wr, m, fr);
;                     f32x4 v0 = acc[ai][bj][m][0], v1 = acc[ai][bj][m][1];
;                     if (rs) {
;                         const float rstd = rsqrtf(rs[r] * (1.f / 1024.f) + EPS);
;                         const float* sp = shw + (size_t)batch_of(r) * INPAD + c0;
;                         v0 = v0 * rstd + *(const f32x4*)sp; v1 = v1 * rstd + *(const f32x4*)(sp + 4);
.LBB0_342:
	s_or_b64 exec, exec, s[54:55]
	v_or_b32_e32 v6, 0x80, v4
	s_movk_i32 s2, 0x720
	v_cmp_gt_i32_e32 vcc, s2, v6
	s_and_saveexec_b64 s[54:55], vcc
	s_cbranch_execz .LBB0_445
	s_lshl_b32 s25, s69, 8
	s_add_i32 s69, s25, s4
	v_or_b32_e32 v76, s69, v141
	v_ashrrev_i32_e32 v77, 31, v76
	s_mov_b64 s[2:3], -1
	s_and_b64 vcc, exec, s[72:73]
	v_cmp_gt_i32_e64 s[40:41], s89, v76
	s_cbranch_vccz .LBB0_345
	v_readlane_b32 s2, v251, 45
	v_readlane_b32 s3, v251, 46
	s_nop 1
	v_lshl_add_u64 v[68:69], v[76:77], 2, s[2:3]
	global_load_dword v78, v[68:69], off
	s_add_i32 s3, s69, 0xffff0000
	s_lshr_b32 s3, s3, 6
	s_ashr_i32 s2, s69, 12
	s_add_i32 s3, s3, 16
	v_mov_b32_e32 v6, s3
	v_mov_b32_e32 v68, s2
	v_cndmask_b32_e64 v68, v6, v68, s[40:41]
	v_ashrrev_i32_e32 v69, 31, v68
	v_lshlrev_b64 v[68:69], 13, v[68:69]
	v_lshl_add_u64 v[68:69], s[56:57], 0, v[68:69]
	v_mov_b32_e32 v6, v4
	v_lshl_add_u64 v[72:73], v[6:7], 2, v[68:69]
	global_load_dwordx4 v[68:71], v[72:73], off offset:512
	s_nop 0
	global_load_dwordx4 v[72:75], v[72:73], off offset:528
	s_mov_b64 s[2:3], 0
	s_waitcnt vmcnt(0)
	v_mov_b32_e32 v240, v68
	v_mov_b32_e32 v241, v69
	v_mov_b32_e32 v242, v70
	v_mov_b32_e32 v243, v71
	v_mov_b32_e32 v244, v72
	v_mov_b32_e32 v245, v73
	v_mov_b32_e32 v246, v74
	v_mov_b32_e32 v247, v75
	v_fmamk_f32 v78, v78, 0x3a800000, v214
	v_mul_f32_e32 v79, 0x4b800000, v78
	v_cmp_gt_f32_e32 vcc, s9, v78
	s_nop 1
	v_cndmask_b32_e32 v78, v78, v79, vcc
	v_rsq_f32_e32 v78, v78
	s_nop 0
	v_mul_f32_e32 v79, 0x45800000, v78
	v_cndmask_b32_e32 v78, v78, v79, vcc
	v_pk_fma_f32 v[70:71], v[66:67], v[78:79], v[70:71] op_sel_hi:[1,0,1]
	v_pk_fma_f32 v[68:69], v[64:65], v[78:79], v[68:69] op_sel_hi:[1,0,1]
	v_pk_fma_f32 v[74:75], v[62:63], v[78:79], v[74:75] op_sel_hi:[1,0,1]
	v_pk_fma_f32 v[72:73], v[60:61], v[78:79], v[72:73] op_sel_hi:[1,0,1]

;     __device__ __forceinline__ void operator()(const f32x4 (&acc)[2][2][4][2], const Unit& u, int wr, int wc, int fr, int fq) const {
;     ...
;                     const int r = EPI_ROW(u, ai, wr, m, fr);
;                     f32x4 v0 = acc[ai][bj][m][0], v1 = acc[ai][bj][m][1];
;                     if (rs) {
;                         const float rstd = rsqrtf(rs[r] * (1.f / 1024.f) + EPS);
;                         const float* sp = shw + (size_t)batch_of(r) * INPAD + c0;
;                         v0 = v0 * rstd + *(const f32x4*)sp; v1 = v1 * rstd + *(const f32x4*)(sp + 4);
.LBB0_355:
	v_or_b32_e32 v60, s69, v154
	v_cndmask_b32_e64 v62, 0, 1, s[72:73]
	v_ashrrev_i32_e32 v61, 31, v60
	v_cmp_ne_u32_e64 s[40:41], 1, v62
	s_andn2_b64 vcc, exec, s[72:73]
	v_cmp_gt_i32_e64 s[42:43], s89, v60
	s_cbranch_vccnz .LBB0_357
	v_readlane_b32 s18, v251, 45
	v_readlane_b32 s19, v251, 46
	s_nop 1
	v_lshl_add_u64 v[62:63], v[60:61], 2, s[18:19]
	s_nop 0
	s_add_i32 s19, s69, 0xffff0000
	s_lshr_b32 s19, s19, 6
	s_ashr_i32 s18, s69, 12
	s_add_i32 s19, s19, 16
	v_mov_b32_e32 v62, s19
	v_mov_b32_e32 v63, s18
	v_cndmask_b32_e64 v62, v62, v63, s[42:43]
	v_ashrrev_i32_e32 v63, 31, v62
	v_lshlrev_b64 v[62:63], 13, v[62:63]
	v_lshl_add_u64 v[62:63], s[56:57], 0, v[62:63]
	v_lshl_add_u64 v[66:67], v[6:7], 2, v[62:63]
	s_nop 0
	s_nop 0
	s_nop 0
	v_mov_b32_e32 v70, v233
	v_mov_b32_e32 v62, v240
	v_mov_b32_e32 v63, v241
	v_mov_b32_e32 v64, v242
	v_mov_b32_e32 v65, v243
	v_mov_b32_e32 v66, v244
	v_mov_b32_e32 v67, v245
	v_mov_b32_e32 v68, v246
	v_mov_b32_e32 v69, v247
	v_fmamk_f32 v70, v70, 0x3a800000, v214
	v_mul_f32_e32 v71, 0x4b800000, v70
	v_cmp_gt_f32_e32 vcc, s9, v70
	s_nop 1
	v_cndmask_b32_e32 v70, v70, v71, vcc
	v_rsq_f32_e32 v70, v70
	s_nop 0
	v_mul_f32_e32 v71, 0x45800000, v70
	v_cndmask_b32_e32 v70, v70, v71, vcc
	v_pk_fma_f32 v[58:59], v[58:59], v[70:71], v[64:65] op_sel_hi:[1,0,1]
	v_pk_fma_f32 v[56:57], v[56:57], v[70:71], v[62:63] op_sel_hi:[1,0,1]
	v_pk_fma_f32 v[54:55], v[54:55], v[70:71], v[68:69] op_sel_hi:[1,0,1]
	v_pk_fma_f32 v[52:53], v[52:53], v[70:71], v[66:67] op_sel_hi:[1,0,1]

;     __device__ __forceinline__ void operator()(const f32x4 (&acc)[2][2][4][2], const Unit& u, int wr, int wc, int fr, int fq) const {
;     ...
;                     const int r = EPI_ROW(u, ai, wr, m, fr);
;                     f32x4 v0 = acc[ai][bj][m][0], v1 = acc[ai][bj][m][1];
;                     if (rs) {
;                         const float rstd = rsqrtf(rs[r] * (1.f / 1024.f) + EPS);
;                         const float* sp = shw + (size_t)batch_of(r) * INPAD + c0;
;                         v0 = v0 * rstd + *(const f32x4*)sp; v1 = v1 * rstd + *(const f32x4*)(sp + 4);
.LBB0_365:
	s_nop 1
	v_or_b32_e32 v52, s69, v155
	v_ashrrev_i32_e32 v53, 31, v52
	s_and_b64 vcc, exec, s[40:41]
	v_cmp_gt_i32_e64 s[44:45], s89, v52
	s_cbranch_vccnz .LBB0_367
	v_readlane_b32 s2, v251, 45
	v_readlane_b32 s3, v251, 46
	s_nop 1
	v_lshl_add_u64 v[54:55], v[52:53], 2, s[2:3]
	s_nop 0
	s_add_i32 s3, s69, 0xffff0000
	s_lshr_b32 s3, s3, 6
	s_ashr_i32 s2, s69, 12
	s_add_i32 s3, s3, 16
	v_mov_b32_e32 v54, s3
	v_mov_b32_e32 v55, s2
	v_cndmask_b32_e64 v54, v54, v55, s[44:45]
	v_ashrrev_i32_e32 v55, 31, v54
	v_lshlrev_b64 v[54:55], 13, v[54:55]
	v_lshl_add_u64 v[54:55], s[56:57], 0, v[54:55]
	v_lshl_add_u64 v[58:59], v[6:7], 2, v[54:55]
	s_nop 0
	s_nop 0
	s_nop 0
	v_mov_b32_e32 v62, v234
	v_mov_b32_e32 v54, v240
	v_mov_b32_e32 v55, v241
	v_mov_b32_e32 v56, v242
	v_mov_b32_e32 v57, v243
	v_mov_b32_e32 v58, v244
	v_mov_b32_e32 v59, v245
	v_mov_b32_e32 v60, v246
	v_mov_b32_e32 v61, v247
	v_fmamk_f32 v62, v62, 0x3a800000, v214
	v_mul_f32_e32 v63, 0x4b800000, v62
	v_cmp_gt_f32_e32 vcc, s9, v62
	s_nop 1
	v_cndmask_b32_e32 v62, v62, v63, vcc
	v_rsq_f32_e32 v62, v62
	s_nop 0
	v_mul_f32_e32 v63, 0x45800000, v62
	v_cndmask_b32_e32 v62, v62, v63, vcc
	v_pk_fma_f32 v[50:51], v[50:51], v[62:63], v[56:57] op_sel_hi:[1,0,1]
	v_pk_fma_f32 v[48:49], v[48:49], v[62:63], v[54:55] op_sel_hi:[1,0,1]
	v_pk_fma_f32 v[46:47], v[46:47], v[62:63], v[60:61] op_sel_hi:[1,0,1]
	v_pk_fma_f32 v[44:45], v[44:45], v[62:63], v[58:59] op_sel_hi:[1,0,1]

;     __device__ __forceinline__ void operator()(const f32x4 (&acc)[2][2][4][2], const Unit& u, int wr, int wc, int fr, int fq) const {
;     ...
;                     const int r = EPI_ROW(u, ai, wr, m, fr);
;                     f32x4 v0 = acc[ai][bj][m][0], v1 = acc[ai][bj][m][1];
;                     if (rs) {
;                         const float rstd = rsqrtf(rs[r] * (1.f / 1024.f) + EPS);
;                         const float* sp = shw + (size_t)batch_of(r) * INPAD + c0;
;                         v0 = v0 * rstd + *(const f32x4*)sp; v1 = v1 * rstd + *(const f32x4*)(sp + 4);
.LBB0_375:
	s_nop 1
	v_or_b32_e32 v44, s69, v156
	v_ashrrev_i32_e32 v45, 31, v44
	s_and_b64 vcc, exec, s[40:41]
	v_cmp_gt_i32_e64 s[44:45], s89, v44
	s_cbranch_vccnz .LBB0_377
	v_readlane_b32 s2, v251, 45
	v_readlane_b32 s3, v251, 46
	s_nop 1
	v_lshl_add_u64 v[46:47], v[44:45], 2, s[2:3]
	s_nop 0
	s_add_i32 s3, s69, 0xffff0000
	s_lshr_b32 s3, s3, 6
	s_ashr_i32 s2, s69, 12
	s_add_i32 s3, s3, 16
	v_mov_b32_e32 v46, s3
	v_mov_b32_e32 v47, s2
	v_cndmask_b32_e64 v46, v46, v47, s[44:45]
	v_ashrrev_i32_e32 v47, 31, v46
	v_lshlrev_b64 v[46:47], 13, v[46:47]
	v_lshl_add_u64 v[46:47], s[56:57], 0, v[46:47]
	v_lshl_add_u64 v[50:51], v[6:7], 2, v[46:47]
	s_nop 0
	s_nop 0
	s_nop 0
	v_mov_b32_e32 v54, v235
	v_mov_b32_e32 v46, v240
	v_mov_b32_e32 v47, v241
	v_mov_b32_e32 v48, v242
	v_mov_b32_e32 v49, v243
	v_mov_b32_e32 v50, v244
	v_mov_b32_e32 v51, v245
	v_mov_b32_e32 v52, v246
	v_mov_b32_e32 v53, v247
	v_fmamk_f32 v54, v54, 0x3a800000, v214
	v_mul_f32_e32 v55, 0x4b800000, v54
	v_cmp_gt_f32_e32 vcc, s9, v54
	s_nop 1
	v_cndmask_b32_e32 v54, v54, v55, vcc
	v_rsq_f32_e32 v54, v54
	s_nop 0
	v_mul_f32_e32 v55, 0x45800000, v54
	v_cndmask_b32_e32 v54, v54, v55, vcc
	v_pk_fma_f32 v[42:43], v[42:43], v[54:55], v[48:49] op_sel_hi:[1,0,1]
	v_pk_fma_f32 v[40:41], v[40:41], v[54:55], v[46:47] op_sel_hi:[1,0,1]
	v_pk_fma_f32 v[38:39], v[38:39], v[54:55], v[52:53] op_sel_hi:[1,0,1]
	v_pk_fma_f32 v[36:37], v[36:37], v[54:55], v[50:51] op_sel_hi:[1,0,1]

;     __device__ __forceinline__ void operator()(const f32x4 (&acc)[2][2][4][2], const Unit& u, int wr, int wc, int fr, int fq) const {
;     ...
;                     const int r = EPI_ROW(u, ai, wr, m, fr);
;                     f32x4 v0 = acc[ai][bj][m][0], v1 = acc[ai][bj][m][1];
;                     if (rs) {
;                         const float rstd = rsqrtf(rs[r] * (1.f / 1024.f) + EPS);
;                         const float* sp = shw + (size_t)batch_of(r) * INPAD + c0;
;                         v0 = v0 * rstd + *(const f32x4*)sp; v1 = v1 * rstd + *(const f32x4*)(sp + 4);
.LBB0_395:
	s_or_b64 exec, exec, s[44:45]
	s_add_i32 s10, s25, s77
	v_or_b32_e32 v36, s10, v141
	v_ashrrev_i32_e32 v37, 31, v36
	s_and_b64 vcc, exec, s[40:41]
	v_cmp_gt_i32_e64 s[44:45], s89, v36
	s_cbranch_vccnz .LBB0_397
	v_readlane_b32 s18, v251, 45
	v_readlane_b32 s19, v251, 46
	s_nop 1
	v_lshl_add_u64 v[38:39], v[36:37], 2, s[18:19]
	s_nop 0
	s_add_i32 s19, s10, 0xffff0000
	s_lshr_b32 s19, s19, 6
	s_ashr_i32 s18, s10, 12
	s_add_i32 s19, s19, 16
	v_mov_b32_e32 v38, s19
	v_mov_b32_e32 v39, s18
	v_cndmask_b32_e64 v38, v38, v39, s[44:45]
	v_ashrrev_i32_e32 v39, 31, v38
	v_lshlrev_b64 v[38:39], 13, v[38:39]
	v_lshl_add_u64 v[38:39], s[56:57], 0, v[38:39]
	v_lshl_add_u64 v[42:43], v[6:7], 2, v[38:39]
	s_nop 0
	s_nop 0
	s_nop 0
	v_mov_b32_e32 v46, v236
	v_mov_b32_e32 v38, v240
	v_mov_b32_e32 v39, v241
	v_mov_b32_e32 v40, v242
	v_mov_b32_e32 v41, v243
	v_mov_b32_e32 v42, v244
	v_mov_b32_e32 v43, v245
	v_mov_b32_e32 v44, v246
	v_mov_b32_e32 v45, v247
	v_fmamk_f32 v46, v46, 0x3a800000, v214
	v_mul_f32_e32 v47, 0x4b800000, v46
	v_cmp_gt_f32_e32 vcc, s9, v46
	s_nop 1
	v_cndmask_b32_e32 v46, v46, v47, vcc
	v_rsq_f32_e32 v46, v46
	s_nop 0
	v_mul_f32_e32 v47, 0x45800000, v46
	v_cndmask_b32_e32 v46, v46, v47, vcc
	v_pk_fma_f32 v[34:35], v[34:35], v[46:47], v[40:41] op_sel_hi:[1,0,1]
	v_pk_fma_f32 v[32:33], v[32:33], v[46:47], v[38:39] op_sel_hi:[1,0,1]
	v_pk_fma_f32 v[30:31], v[30:31], v[46:47], v[44:45] op_sel_hi:[1,0,1]
	v_pk_fma_f32 v[28:29], v[28:29], v[46:47], v[42:43] op_sel_hi:[1,0,1]

;     __device__ __forceinline__ void operator()(const f32x4 (&acc)[2][2][4][2], const Unit& u, int wr, int wc, int fr, int fq) const {
;     ...
;                     const int r = EPI_ROW(u, ai, wr, m, fr);
;                     f32x4 v0 = acc[ai][bj][m][0], v1 = acc[ai][bj][m][1];
;                     if (rs) {
;                         const float rstd = rsqrtf(rs[r] * (1.f / 1024.f) + EPS);
;                         const float* sp = shw + (size_t)batch_of(r) * INPAD + c0;
;                         v0 = v0 * rstd + *(const f32x4*)sp; v1 = v1 * rstd + *(const f32x4*)(sp + 4);
.LBB0_405:
	s_nop 1
	v_or_b32_e32 v28, s10, v154
	v_ashrrev_i32_e32 v29, 31, v28
	s_and_b64 vcc, exec, s[40:41]
	v_cmp_gt_i32_e64 s[44:45], s89, v28
	s_cbranch_vccnz .LBB0_407
	v_readlane_b32 s18, v251, 45
	v_readlane_b32 s19, v251, 46
	s_nop 1
	v_lshl_add_u64 v[30:31], v[28:29], 2, s[18:19]
	s_nop 0
	s_add_i32 s19, s10, 0xffff0000
	s_lshr_b32 s19, s19, 6
	s_ashr_i32 s18, s10, 12
	s_add_i32 s19, s19, 16
	v_mov_b32_e32 v30, s19
	v_mov_b32_e32 v31, s18
	v_cndmask_b32_e64 v30, v30, v31, s[44:45]
	v_ashrrev_i32_e32 v31, 31, v30
	v_lshlrev_b64 v[30:31], 13, v[30:31]
	v_lshl_add_u64 v[30:31], s[56:57], 0, v[30:31]
	v_lshl_add_u64 v[34:35], v[6:7], 2, v[30:31]
	s_nop 0
	s_nop 0
	s_nop 0
	v_mov_b32_e32 v38, v237
	v_mov_b32_e32 v30, v240
	v_mov_b32_e32 v31, v241
	v_mov_b32_e32 v32, v242
	v_mov_b32_e32 v33, v243
	v_mov_b32_e32 v34, v244
	v_mov_b32_e32 v35, v245
	v_mov_b32_e32 v36, v246
	v_mov_b32_e32 v37, v247
	v_fmamk_f32 v38, v38, 0x3a800000, v214
	v_mul_f32_e32 v39, 0x4b800000, v38
	v_cmp_gt_f32_e32 vcc, s9, v38
	s_nop 1
	v_cndmask_b32_e32 v38, v38, v39, vcc
	v_rsq_f32_e32 v38, v38
	s_nop 0
	v_mul_f32_e32 v39, 0x45800000, v38
	v_cndmask_b32_e32 v38, v38, v39, vcc
	v_pk_fma_f32 v[26:27], v[26:27], v[38:39], v[32:33] op_sel_hi:[1,0,1]
	v_pk_fma_f32 v[24:25], v[24:25], v[38:39], v[30:31] op_sel_hi:[1,0,1]
	v_pk_fma_f32 v[22:23], v[22:23], v[38:39], v[36:37] op_sel_hi:[1,0,1]
	v_pk_fma_f32 v[20:21], v[20:21], v[38:39], v[34:35] op_sel_hi:[1,0,1]

;     __device__ __forceinline__ void operator()(const f32x4 (&acc)[2][2][4][2], const Unit& u, int wr, int wc, int fr, int fq) const {
;     ...
;                     const int r = EPI_ROW(u, ai, wr, m, fr);
;                     f32x4 v0 = acc[ai][bj][m][0], v1 = acc[ai][bj][m][1];
;                     if (rs) {
;                         const float rstd = rsqrtf(rs[r] * (1.f / 1024.f) + EPS);
;                         const float* sp = shw + (size_t)batch_of(r) * INPAD + c0;
;                         v0 = v0 * rstd + *(const f32x4*)sp; v1 = v1 * rstd + *(const f32x4*)(sp + 4);
.LBB0_415:
	s_nop 1
	v_or_b32_e32 v20, s10, v155
	v_ashrrev_i32_e32 v21, 31, v20
	s_and_b64 vcc, exec, s[40:41]
	v_cmp_gt_i32_e64 s[44:45], s89, v20
	s_cbranch_vccnz .LBB0_417
	v_readlane_b32 s18, v251, 45
	v_readlane_b32 s19, v251, 46
	s_nop 1
	v_lshl_add_u64 v[22:23], v[20:21], 2, s[18:19]
	s_nop 0
	s_add_i32 s19, s10, 0xffff0000
	s_lshr_b32 s19, s19, 6
	s_ashr_i32 s18, s10, 12
	s_add_i32 s19, s19, 16
	v_mov_b32_e32 v22, s19
	v_mov_b32_e32 v23, s18
	v_cndmask_b32_e64 v22, v22, v23, s[44:45]
	v_ashrrev_i32_e32 v23, 31, v22
	v_lshlrev_b64 v[22:23], 13, v[22:23]
	v_lshl_add_u64 v[22:23], s[56:57], 0, v[22:23]
	v_lshl_add_u64 v[26:27], v[6:7], 2, v[22:23]
	s_nop 0
	s_nop 0
	s_nop 0
	v_mov_b32_e32 v30, v238
	v_mov_b32_e32 v22, v240
	v_mov_b32_e32 v23, v241
	v_mov_b32_e32 v24, v242
	v_mov_b32_e32 v25, v243
	v_mov_b32_e32 v26, v244
	v_mov_b32_e32 v27, v245
	v_mov_b32_e32 v28, v246
	v_mov_b32_e32 v29, v247
	v_fmamk_f32 v30, v30, 0x3a800000, v214
	v_mul_f32_e32 v31, 0x4b800000, v30
	v_cmp_gt_f32_e32 vcc, s9, v30
	s_nop 1
	v_cndmask_b32_e32 v30, v30, v31, vcc
	v_rsq_f32_e32 v30, v30
	s_nop 0
	v_mul_f32_e32 v31, 0x45800000, v30
	v_cndmask_b32_e32 v30, v30, v31, vcc
	v_pk_fma_f32 v[18:19], v[18:19], v[30:31], v[24:25] op_sel_hi:[1,0,1]
	v_pk_fma_f32 v[16:17], v[16:17], v[30:31], v[22:23] op_sel_hi:[1,0,1]
	v_pk_fma_f32 v[14:15], v[14:15], v[30:31], v[28:29] op_sel_hi:[1,0,1]
	v_pk_fma_f32 v[12:13], v[12:13], v[30:31], v[26:27] op_sel_hi:[1,0,1]

;     __device__ __forceinline__ void operator()(const f32x4 (&acc)[2][2][4][2], const Unit& u, int wr, int wc, int fr, int fq) const {
;     ...
;                     const int r = EPI_ROW(u, ai, wr, m, fr);
;                     f32x4 v0 = acc[ai][bj][m][0], v1 = acc[ai][bj][m][1];
;                     if (rs) {
;                         const float rstd = rsqrtf(rs[r] * (1.f / 1024.f) + EPS);
;                         const float* sp = shw + (size_t)batch_of(r) * INPAD + c0;
;                         v0 = v0 * rstd + *(const f32x4*)sp; v1 = v1 * rstd + *(const f32x4*)(sp + 4);
.LBB0_425:
	s_nop 1
	v_or_b32_e32 v12, s10, v156
	v_ashrrev_i32_e32 v13, 31, v12
	s_and_b64 vcc, exec, s[40:41]
	v_cmp_gt_i32_e64 s[40:41], s89, v12
	s_cbranch_vccnz .LBB0_427
	v_readlane_b32 s6, v251, 45
	v_readlane_b32 s7, v251, 46
	s_nop 1
	v_lshl_add_u64 v[14:15], v[12:13], 2, s[6:7]
	s_nop 0
	s_add_i32 s7, s10, 0xffff0000
	s_lshr_b32 s7, s7, 6
	s_ashr_i32 s6, s10, 12
	s_add_i32 s7, s7, 16
	v_mov_b32_e32 v14, s7
	v_mov_b32_e32 v15, s6
	v_cndmask_b32_e64 v14, v14, v15, s[40:41]
	v_ashrrev_i32_e32 v15, 31, v14
	v_lshlrev_b64 v[14:15], 13, v[14:15]
	v_lshl_add_u64 v[14:15], s[56:57], 0, v[14:15]
	v_lshl_add_u64 v[18:19], v[6:7], 2, v[14:15]
	s_nop 0
	s_nop 0
	s_nop 0
	v_mov_b32_e32 v22, v239
	v_mov_b32_e32 v14, v240
	v_mov_b32_e32 v15, v241
	v_mov_b32_e32 v16, v242
	v_mov_b32_e32 v17, v243
	v_mov_b32_e32 v18, v244
	v_mov_b32_e32 v19, v245
	v_mov_b32_e32 v20, v246
	v_mov_b32_e32 v21, v247
	v_fmamk_f32 v22, v22, 0x3a800000, v214
	v_mul_f32_e32 v23, 0x4b800000, v22
	v_cmp_gt_f32_e32 vcc, s9, v22
	s_nop 1
	v_cndmask_b32_e32 v22, v22, v23, vcc
	v_rsq_f32_e32 v22, v22
	s_nop 0
	v_mul_f32_e32 v23, 0x45800000, v22
	v_cndmask_b32_e32 v22, v22, v23, vcc
	v_pk_fma_f32 v[10:11], v[10:11], v[22:23], v[16:17] op_sel_hi:[1,0,1]
	v_pk_fma_f32 v[8:9], v[8:9], v[22:23], v[14:15] op_sel_hi:[1,0,1]
	v_pk_fma_f32 v[2:3], v[2:3], v[22:23], v[20:21] op_sel_hi:[1,0,1]
	v_pk_fma_f32 v[0:1], v[0:1], v[22:23], v[18:19] op_sel_hi:[1,0,1]

; __device__ __forceinline__ void softmax_def(f32x16& p0, f32x16& p1, bool first, float cb, float& mref, f32x16& negm, float& l, f32x16& oa, f32x16& ob) {
;     float a = fmaxf(fmaxf(p0[0], p0[1]), p1[0]), b = fmaxf(fmaxf(p0[2], p0[3]), p1[1]);
;     a = fmaxf(fmaxf(a, p1[2]), p1[3]);
; #pragma unroll
;     for (int r = 4; r < 16; r += 4) { a = fmaxf(fmaxf(a, p0[r]), p0[r + 1]); b = fmaxf(fmaxf(b, p0[r + 2]), p0[r + 3]); a = fmaxf(fmaxf(a, p1[r]), p1[r + 1]); b = fmaxf(fmaxf(b, p1[r + 2]), p1[r + 3]); }
;     const float rm = xhalf_max(fmaxf(a, b));
; template <int MODE>
; __device__ __forceinline__ void attn_unit(LAS unsigned char* lds, const Ptrs& P, int nq, int nt_block, int qpos0, bool sample, int h,
;                                           const float* relb  , const float* lamp, const float* subg, bf16_t* Obase  , int wv) {
;     ...
;                     p0 = __builtin_amdgcn_mfma_f32_32x32x16_bf16(kf[2], qf[1], p0, 0, 0, 0);
;                     p1 = __builtin_amdgcn_mfma_f32_32x32x16_bf16(kf[3], qf[1], p1, 0, 0, 0);
; #pragma unroll
;                     for (int ks = 0; ks < 2; ++ks) { kg2[2 * ks] = *(const LAS bf16x8*)(kb + 4096 + ks * 2048); kg2[2 * ks + 1] = *(const LAS bf16x8*)(kb + 4096 + ks * 2048 + 512); }
;                     softmax_def(p0, p1, first, cbias, mr1, ng1, l1, o1a, o1b);
;                     pack_p(p0, p1, pa);
;                 }
;                 bf16x8 vf[8];
;                 {
;                     f32x16 s0, s1;
;                     if (farT) {
;                         s0 = __builtin_amdgcn_mfma_f32_32x32x16_bf16(kg2[0], qf[2], ng2, 0, 0, 0);
;                         s1 = __builtin_amdgcn_mfma_f32_32x32x16_bf16(kg2[1], qf[2], ng2, 0, 0, 0);
;                     } else {
;                         const float nb = ng2[0] - cbias;
; #pragma unroll
;                         for (int r = 0; r < 16; ++r) { const int idx = ib + (r & 3) + 8 * (r >> 2); s0[r] = bt[idx] + nb; s1[r] = bt[idx + 32] + nb; }
;                         s0 = __builtin_amdgcn_mfma_f32_32x32x16_bf16(kg2[0], qf[2], s0, 0, 0, 0);
;                         s1 = __builtin_amdgcn_mfma_f32_32x32x16_bf16(kg2[1], qf[2], s1, 0, 0, 0);
;                     }
;                     s0 = __builtin_amdgcn_mfma_f32_32x32x16_bf16(kg2[2], qf[3], s0, 0, 0, 0);
;                     s1 = __builtin_amdgcn_mfma_f32_32x32x16_bf16(kg2[3], qf[3], s1, 0, 0, 0);
.LBB0_1231:
	s_waitcnt lgkmcnt(1)
	v_mfma_f32_32x32x16_bf16 v[118:133], v[72:75], v[182:185], v[118:133]
	ds_read_b128 v[80:83], v4 offset:4096
	ds_read_b128 v[210:213], v4 offset:4608
	ds_read_b128 v[76:79], v4 offset:6144
	ds_read_b128 v[72:75], v4 offset:6656
	s_cmp_eq_u32 s28, 0
	s_cselect_b64 s[24:25], -1, 0
	s_cmp_lg_u32 s28, 0
	s_cselect_b64 s[2:3], -1, 0
	s_and_b64 vcc, exec, s[2:3]
	s_nop 2
	v_max_f32_e32 v4, v119, v119
	s_waitcnt lgkmcnt(4)
	v_mfma_f32_32x32x16_bf16 v[134:149], v[150:153], v[182:185], v[134:149]
	s_cmp_lg_u64 s[26:27], 0
	s_cbranch_scc1 .Lqk2h_skip_p
	s_waitcnt lgkmcnt(3)
	v_mfma_f32_32x32x16_bf16 v[166:181], v[80:83], v[186:189], v[86:101]
	s_waitcnt lgkmcnt(2)
	v_mfma_f32_32x32x16_bf16 v[150:165], v[210:213], v[186:189], v[86:101]
	s_waitcnt lgkmcnt(1)
	v_mfma_f32_32x32x16_bf16 v[166:181], v[76:79], v[190:193], v[166:181]
	s_waitcnt lgkmcnt(0)
	v_mfma_f32_32x32x16_bf16 v[150:165], v[72:75], v[190:193], v[150:165]
.Lqk2h_skip_p:
	v_max_f32_e32 v85, v118, v118
	v_max_f32_e32 v4, v85, v4
	s_nop 9
	v_max3_f32 v85, v120, v121, v135
	v_max3_f32 v4, v4, v134, v136
	v_max3_f32 v4, v4, v137, v122
	v_max3_f32 v85, v85, v124, v125
	v_max3_f32 v4, v4, v123, v138
	v_max3_f32 v85, v85, v140, v141
	v_max3_f32 v4, v4, v139, v126
	v_max3_f32 v85, v85, v128, v129
	v_max3_f32 v4, v4, v127, v142
	v_max3_f32 v85, v85, v144, v145
	v_max3_f32 v4, v4, v143, v130
	v_max3_f32 v85, v85, v132, v133
	v_max3_f32 v4, v4, v131, v146
	v_max3_f32 v85, v85, v148, v149
	v_max3_f32 v4, v4, v147, v85
	v_mov_b32_e32 v85, v4
	s_nop 1
	v_permlane32_swap_b32_e32 v4, v85
	v_max_f32_e32 v85, v85, v85
	v_max_f32_e32 v4, v4, v4
	v_max_f32_e32 v85, v4, v85
	s_cbranch_vccz .LBB0_1236
	v_cmp_lt_f32_e32 vcc, s76, v85
	s_mov_b64 s[30:31], 0
	s_mov_b64 s[28:29], 0
	s_cbranch_vccz .LBB0_1234
	v_max_f32_e32 v4, v85, v85
	v_max_f32_e32 v4, 0, v4
	s_mov_b64 s[28:29], -1

; template <int MODE>
; __device__ __forceinline__ void attn_unit(LAS unsigned char* lds, const Ptrs& P, int nq, int nt_block, int qpos0, bool sample, int h,
;                                           const float* relb  , const float* lamp, const float* subg, bf16_t* Obase  , int wv) {
;     ...
;                     if (farT) {
;                         s0 = __builtin_amdgcn_mfma_f32_32x32x16_bf16(kg2[0], qf[2], ng2, 0, 0, 0);
;                         s1 = __builtin_amdgcn_mfma_f32_32x32x16_bf16(kg2[1], qf[2], ng2, 0, 0, 0);
;                     } else {
;                         const float nb = ng2[0] - cbias;
; #pragma unroll
;                         for (int r = 0; r < 16; ++r) { const int idx = ib + (r & 3) + 8 * (r >> 2); s0[r] = bt[idx] + nb; s1[r] = bt[idx + 32] + nb; }
;                         s0 = __builtin_amdgcn_mfma_f32_32x32x16_bf16(kg2[0], qf[2], s0, 0, 0, 0);
;                         s1 = __builtin_amdgcn_mfma_f32_32x32x16_bf16(kg2[1], qf[2], s1, 0, 0, 0);
;                     }
;                     s0 = __builtin_amdgcn_mfma_f32_32x32x16_bf16(kg2[2], qf[3], s0, 0, 0, 0);
;                     s1 = __builtin_amdgcn_mfma_f32_32x32x16_bf16(kg2[3], qf[3], s1, 0, 0, 0);
;                     softmax_def(s0, s1, first, cbias, mr2, ng2, l2, o2a, o2b);
.LBB0_1241:
	s_and_b64 vcc, exec, s[2:3]
	s_branch .Lqk2h_done_p

; __device__ __forceinline__ float xhalf_max(float m) { auto rr = __builtin_amdgcn_permlane32_swap(__float_as_uint(m), __float_as_uint(m), false, false); return fmaxf(__uint_as_float(rr[0]), __uint_as_float(rr[1])); }
; __device__ __forceinline__ void softmax_def(f32x16& p0, f32x16& p1, bool first, float cb, float& mref, f32x16& negm, float& l, f32x16& oa, f32x16& ob) {
;     float a = fmaxf(fmaxf(p0[0], p0[1]), p1[0]), b = fmaxf(fmaxf(p0[2], p0[3]), p1[1]);
;     a = fmaxf(fmaxf(a, p1[2]), p1[3]);
; #pragma unroll
;     for (int r = 4; r < 16; r += 4) { a = fmaxf(fmaxf(a, p0[r]), p0[r + 1]); b = fmaxf(fmaxf(b, p0[r + 2]), p0[r + 3]); a = fmaxf(fmaxf(a, p1[r]), p1[r + 1]); b = fmaxf(fmaxf(b, p1[r + 2]), p1[r + 3]); }
;     const float rm = xhalf_max(fmaxf(a, b));
;     if (first || __any(rm > 16.f)) {
.Lqk2h_done_p:
	s_nop 8
	v_max_f32_e32 v4, v167, v167
	v_max_f32_e32 v76, v166, v166
	v_max_f32_e32 v4, v76, v4
	v_max3_f32 v72, v168, v169, v151
	v_max3_f32 v4, v4, v150, v152
	v_max3_f32 v4, v4, v153, v170
	v_max3_f32 v72, v72, v172, v173
	v_max3_f32 v4, v4, v171, v154
	v_max3_f32 v72, v72, v156, v157
	v_max3_f32 v4, v4, v155, v174
	v_max3_f32 v72, v72, v176, v177
	v_max3_f32 v4, v4, v175, v158
	v_max3_f32 v72, v72, v160, v161
	v_max3_f32 v4, v4, v159, v178
	v_max3_f32 v72, v72, v180, v181
	v_max3_f32 v4, v4, v179, v162
	v_max3_f32 v72, v72, v164, v165
	v_max3_f32 v4, v4, v163, v72
	v_mov_b32_e32 v72, v4
	s_nop 1
	v_permlane32_swap_b32_e32 v4, v72
	v_max_f32_e32 v72, v72, v72
	v_max_f32_e32 v4, v4, v4
	v_max_f32_e32 v72, v4, v72
	s_cbranch_vccz .LBB0_1251
	v_cmp_lt_f32_e32 vcc, s76, v72
	s_mov_b64 s[26:27], 0
	s_mov_b64 s[2:3], 0
	s_cbranch_vccz .LBB0_1246
	v_max_f32_e32 v4, v72, v72
	v_max_f32_e32 v4, 0, v4
	s_mov_b64 s[2:3], -1
